# attention-projection GEMM: first tile's stage loads issued at the start of the seam after mLSTM (same early-stage idea as the merge GEMM)
# speedup vs baseline: 1.0103x; 1.0012x over previous
; #define PG8_STAGE(bufoff, gbase, voff) do { _Pragma("unroll") for (int _i = 0; _i < 2; ++_i) \
;         __builtin_amdgcn_global_load_lds((const unsigned*)((const char*)(gbase) + (voff)[_i]), (LAS unsigned*)(lds + (bufoff) + ldsw + _i * 8192), 16, 0, 0); } while (0)
;     __device__ bool next(int i, Unit& u) const {
;         const long L = (long)i * G + c; if (L >= nwg) return false;
;         int wgid = (int)L; { const int q = nwg / NXCD, r = nwg % NXCD, xcd = wgid % NXCD, off = wgid / NXCD; wgid = (xcd < r ? xcd * (q + 1) : r * (q + 1) + (xcd - r) * q) + off; }
;         const int nig = WGM * nN, gid = wgid / nig, fm = gid * WGM, gsz = (nM - fm) < WGM ? (nM - fm) : WGM;
;         u.pm = fm + ((wgid % nig) % gsz); u.pn = (wgid % nig) / gsz; return true;
; template <class Epi, bool AFTER = false>
; __device__ __forceinline__ void gemm_phase(LAS unsigned char* lds, const Gemm g, const StaticOrder& S, const Epi& E) {
;     const int tid = threadIdx.x, wid = __builtin_amdgcn_readfirstlane(tid >> 6), lane = tid & 63, wr = wid >> 2, wc = wid & 3, fr = lane & 15, fq = lane >> 4;
;     const int K = g.K, nt = K / BK;
;     unsigned voffA[2], voffB[2];
; #pragma unroll
;     for (int i = 0; i < 2; ++i) { int R, C; stage_rc(tid * 16 + i * 8192, R, C); const int Rb = (R & ~31) + perm32(R & 31);
;         voffA[i] = (unsigned)(R * K + C) * 2u; voffB[i] = (unsigned)(Rb * K + C) * 2u; }
;     const size_t kstep = (size_t)(BK * 2);
;     const size_t hstep = (size_t)HALF * K * 2;
;     const size_t tstep = 2 * hstep;
;     const unsigned ldsw = (unsigned)wid * 1024u;
;     const int aoff = lds_byte(wr * 64 + fr, fq * 8), boff = lds_byte(wc * 32 + fr, fq * 8);
;     ...
;     Unit cur, nxt; int ui = 0;
;     if (!S.next(0, cur)) return;
;     f32x4 acc[2][2][4][2];
; #pragma unroll
;     for (int a = 0; a < 2; ++a)
; #pragma unroll
;         for (int b = 0; b < 2; ++b)
; #pragma unroll
;             for (int m = 0; m < 4; ++m)
; #pragma unroll
;                 for (int n = 0; n < 2; ++n) acc[a][b][m][n] = (f32x4){0.f, 0.f, 0.f, 0.f};
;     bf16x8 At[4][2], B0[2][2], B1[2][2];
;     const char* cA = (const char*)g.A + (size_t)cur.pm * tstep; const char* cB = (const char*)g.Bt + (size_t)cur.pn * tstep;
;     PG8_STAGE(PG8_SB(0, 0), cB, voffB); PG8_STAGE(PG8_SA(0, 0), cA, voffA); PG8_STAGE(PG8_SB(0, 1), cB + hstep, voffB); PG8_STAGE(PG8_SA(0, 1), cA + hstep, voffA);
.LBB0_359:
	s_mov_b32 s100, 0
	s_cmp_gt_i32 s91, 4
	v_readlane_b32 s2, v254, 25
	s_cselect_b64 s[0:1], -1, 0
	v_readlane_b32 s3, v254, 26
	s_and_b64 s[2:3], s[2:3], s[0:1]
	s_andn2_b64 vcc, exec, s[2:3]
	s_cbranch_vccnz .LBB0_409
	s_mov_b32 s100, 1
	s_cmpk_lt_i32 s84, 0x700
	s_cselect_b64 s[2:3], -1, 0
	s_cmpk_gt_i32 s84, 0x6ff
	v_readfirstlane_b32 s33, v212
	s_cbranch_scc1 .Lp4e_412
	s_ashr_i32 s4, s84, 31
	s_lshr_b32 s4, s4, 29
	s_add_i32 s4, s84, s4
	s_ashr_i32 s5, s4, 3
	s_and_b32 s4, s4, -8
	s_sub_i32 s4, s84, s4
	s_cmp_lt_i32 s4, 0
	s_movk_i32 s6, 0xe1
	s_cselect_b32 s6, s6, 0xe0
	s_mul_i32 s4, s4, s6
	s_add_i32 s4, s4, s5
	s_mul_hi_i32 s5, s4, 0x92492493
	s_add_i32 s5, s5, s4
	s_lshr_b32 s6, s5, 31
	s_ashr_i32 s5, s5, 6
	s_add_i32 s5, s5, s6
	s_lshl_b32 s6, s5, 2
	s_mulk_i32 s5, 0x70
	s_sub_i32 s4, s4, s5
	s_bfe_i32 s5, s4, 0x80000
	s_bfe_u32 s5, s5, 0x2000d
	s_add_i32 s5, s4, s5
	s_bfe_i32 s7, s5, 0x80000
	s_and_b32 s5, s5, 0xfc
	s_sub_i32 s4, s4, s5
	s_sext_i32_i16 s7, s7
	s_sext_i32_i8 s4, s4
	s_add_i32 s6, s6, s4
	s_ashr_i32 s4, s7, 2
.Lp4e_412:
	s_andn2_b64 vcc, exec, s[2:3]
	s_cbranch_vccnz .Lp4e_fail
	v_lshrrev_b32_e32 v2, 1, v212
	v_and_b32_e32 v11, 24, v2
	v_lshrrev_b32_e32 v2, 5, v212
	v_and_b32_e32 v2, 4, v2
	v_bfe_u32 v3, v212, 2, 2
	v_lshlrev_b32_e32 v0, 4, v212
	v_and_b32_e32 v1, 32, v212
	v_bfe_u32 v10, v212, 2, 4
	v_or3_b32 v2, v2, v3, v11
	v_lshrrev_b32_e32 v3, 3, v212
	s_movk_i32 s2, 0x70
	v_bitop3_b32 v8, v0, v1, 48 bitop3:0x6c
	v_and_b32_e32 v9, 64, v212
	v_and_or_b32 v4, v3, s2, v10
	s_movk_i32 s2, 0x60
	v_add_u32_e32 v12, 0x2000, v0
	v_or_b32_e32 v1, v8, v9
	v_and_or_b32 v3, v3, s2, v2
	v_lshrrev_b32_e32 v0, 7, v12
	s_movk_i32 s2, 0xf0
	s_add_u32 s40, s88, 0xa00000
	v_lshl_or_b32 v130, v3, 11, v1
	v_and_or_b32 v3, v0, s2, v10
	s_movk_i32 s2, 0xe0
	s_addc_u32 s41, s89, 0
	v_and_or_b32 v0, v0, s2, v2
	s_lshr_b32 s2, s33, 6
	s_ashr_i32 s7, s6, 31
	s_ashr_i32 s5, s4, 31
	s_lshr_b32 s3, s33, 8
	s_lshl_b32 s42, s2, 10
	s_lshl_b64 s[8:9], s[6:7], 19
	s_lshl_b64 s[10:11], s[4:5], 19
	s_add_u32 s24, s40, s10
	s_addc_u32 s25, s41, s11
	s_add_i32 s43, s42, 0
	s_add_i32 m0, s43, 0x10000
	v_lshl_or_b32 v134, v0, 11, v1
	global_load_lds_dwordx4 v130, s[24:25]
	s_add_i32 m0, s43, 0x12000
	s_add_u32 s22, s74, s8
	v_lshl_or_b32 v128, v4, 11, v1
	global_load_lds_dwordx4 v134, s[24:25]
	s_addc_u32 s23, s75, s9
	s_mov_b32 m0, s43
	s_add_i32 s44, s43, 0x2000
	v_lshl_or_b32 v132, v3, 11, v1
	global_load_lds_dwordx4 v128, s[22:23]
	s_mov_b32 m0, s44
	s_add_u32 s8, s24, 0x40000
	global_load_lds_dwordx4 v132, s[22:23]
	s_addc_u32 s9, s25, 0
	s_add_i32 m0, s43, 0x14000
	v_mov_b32_e32 v137, 0
	global_load_lds_dwordx4 v130, s[8:9]
	s_add_i32 m0, s43, 0x16000
	v_mov_b32_e32 v131, v137
	global_load_lds_dwordx4 v134, s[8:9]
	s_add_u32 s8, s22, 0x40000
	s_addc_u32 s9, s23, 0
	s_add_i32 s45, s43, 0x4000
	s_mov_b32 m0, s45
	s_add_i32 s46, s43, 0x6000
	global_load_lds_dwordx4 v128, s[8:9]
	s_mov_b32 m0, s46
	v_mov_b32_e32 v135, v137
	global_load_lds_dwordx4 v132, s[8:9]
	s_branch .Lp4e_skip
.Lp4e_fail:
	s_mov_b32 s100, 0
.Lp4e_skip:
	s_waitcnt vmcnt(0)
	s_waitcnt vmcnt(0) lgkmcnt(0)
	s_barrier
	s_mov_b64 s[2:3], exec
	v_readlane_b32 s4, v254, 1
	v_readlane_b32 s5, v254, 2
	s_and_b64 s[4:5], s[2:3], s[4:5]
	s_mov_b64 exec, s[4:5]
	s_cbranch_execz .LBB0_408
	v_readlane_b32 s4, v254, 22
	s_waitcnt vmcnt(0) expcnt(0) lgkmcnt(0)
	s_nop 0
	v_mov_b32_e32 v0, s4
	ds_read_b32 v2, v0
	ds_read_b32 v0, v0 offset:4
	s_waitcnt lgkmcnt(1)
	v_cmp_ne_u32_e32 vcc, 0, v2
	s_cbranch_vccnz .LBB0_376
	v_readlane_b32 s4, v254, 0
	s_mul_i32 s33, s83, s4
	s_add_u32 s4, s88, 0xffc0200
	s_addc_u32 s5, s89, 0
	s_add_u32 s6, s88, 0xffc0400
	s_addc_u32 s7, s89, 0
	s_add_u32 s8, s88, 0xffc0500
	s_addc_u32 s9, s89, 0
	s_add_u32 s10, s88, 0xffc0600
	s_addc_u32 s11, s89, 0
	s_add_u32 s12, s88, 0xffc0700
	s_addc_u32 s13, s89, 0
	s_add_u32 s14, s88, 0xffc0800
	s_addc_u32 s15, s89, 0
	s_add_u32 s16, s88, 0xffc0900
	s_addc_u32 s17, s89, 0
	s_add_u32 s18, s88, 0xffc0a00
	s_addc_u32 s19, s89, 0
	s_add_u32 s20, s88, 0xffc0b00
	s_addc_u32 s21, s89, 0
	s_add_u32 s22, s88, 0xffc0c00
	s_addc_u32 s23, s89, 0
	s_add_u32 s24, s88, 0xffc0d00
	s_addc_u32 s25, s89, 0
	s_add_u32 s26, s88, 0xffc0e00
	s_addc_u32 s27, s89, 0
	s_add_u32 s28, s88, 0xffc0f00
	s_addc_u32 s29, s89, 0
	s_add_u32 s30, s88, 0xffc1000
	s_addc_u32 s31, s89, 0
	s_add_u32 s34, s88, 0xffc1100
	s_addc_u32 s35, s89, 0
	s_add_u32 s36, s88, 0xffc1200
	s_addc_u32 s37, s89, 0
	s_add_u32 s38, s88, 0xffc1300
	s_mul_i32 s33, s33, s82
	s_addc_u32 s39, s89, 0
	s_mov_b32 s46, 1
	v_mov_b32_e32 v16, 0
	s_branch .LBB0_364

; #define PG8_STAGE(bufoff, gbase, voff) do { _Pragma("unroll") for (int _i = 0; _i < 2; ++_i) \
;         __builtin_amdgcn_global_load_lds((const unsigned*)((const char*)(gbase) + (voff)[_i]), (LAS unsigned*)(lds + (bufoff) + ldsw + _i * 8192), 16, 0, 0); } while (0)
; #define PG8_WAIT_V(n) asm volatile("s_waitcnt vmcnt(" #n ")" ::: "memory")
; #define PG8_BAR __builtin_amdgcn_s_barrier()
; #define PG8_WAIT_V(n) asm volatile("s_waitcnt vmcnt(" #n ")" ::: "memory")
; #define PG8_BAR __builtin_amdgcn_s_barrier()
; template <class Epi, bool AFTER = false>
; __device__ __forceinline__ void gemm_phase(LAS unsigned char* lds, const Gemm g, const StaticOrder& S, const Epi& E) {
;     ...
;     Unit cur, nxt; int ui = 0;
;     if (!S.next(0, cur)) return;
;     f32x4 acc[2][2][4][2];
; #pragma unroll
;     for (int a = 0; a < 2; ++a)
; #pragma unroll
;         for (int b = 0; b < 2; ++b)
; #pragma unroll
;             for (int m = 0; m < 4; ++m)
; #pragma unroll
;                 for (int n = 0; n < 2; ++n) acc[a][b][m][n] = (f32x4){0.f, 0.f, 0.f, 0.f};
;     bf16x8 At[4][2], B0[2][2], B1[2][2];
;     const char* cA = (const char*)g.A + (size_t)cur.pm * tstep; const char* cB = (const char*)g.Bt + (size_t)cur.pn * tstep;
;     PG8_STAGE(PG8_SB(0, 0), cB, voffB); PG8_STAGE(PG8_SA(0, 0), cA, voffA); PG8_STAGE(PG8_SB(0, 1), cB + hstep, voffB); PG8_STAGE(PG8_SA(0, 1), cA + hstep, voffA);
;     if (wr == 1) PG8_BAR;
;     PG8_WAIT_V(4); PG8_BAR;
;     PG8_STAGE(PG8_SB(1, 0), cB + kstep, voffB); PG8_STAGE(PG8_SA(1, 0), cA + kstep, voffA); PG8_STAGE(PG8_SB(1, 1), cB + hstep + kstep, voffB);
;     PG8_WAIT_V(6); PG8_BAR;
.LBB0_409:
	s_cmp_lt_i32 s90, 5
	s_cselect_b64 s[2:3], -1, 0
	s_and_b64 s[0:1], s[2:3], s[0:1]
	s_andn2_b64 vcc, exec, s[0:1]
	s_cbranch_vccnz .LBB0_520
	s_cmp_eq_u32 s100, 1
	s_cbranch_scc1 .Lp4n_start
	s_cmpk_lt_i32 s84, 0x700
	s_cselect_b64 s[2:3], -1, 0
	s_cmpk_gt_i32 s84, 0x6ff
	v_readfirstlane_b32 s33, v212
	s_cbranch_scc1 .LBB0_412
	s_ashr_i32 s4, s84, 31
	s_lshr_b32 s4, s4, 29
	s_add_i32 s4, s84, s4
	s_ashr_i32 s5, s4, 3
	s_and_b32 s4, s4, -8
	s_sub_i32 s4, s84, s4
	s_cmp_lt_i32 s4, 0
	s_movk_i32 s6, 0xe1
	s_cselect_b32 s6, s6, 0xe0
	s_mul_i32 s4, s4, s6
	s_add_i32 s4, s4, s5
	s_mul_hi_i32 s5, s4, 0x92492493
	s_add_i32 s5, s5, s4
	s_lshr_b32 s6, s5, 31
	s_ashr_i32 s5, s5, 6
	s_add_i32 s5, s5, s6
	s_lshl_b32 s6, s5, 2
	s_mulk_i32 s5, 0x70
	s_sub_i32 s4, s4, s5
	s_bfe_i32 s5, s4, 0x80000
	s_bfe_u32 s5, s5, 0x2000d
	s_add_i32 s5, s4, s5
	s_bfe_i32 s7, s5, 0x80000
	s_and_b32 s5, s5, 0xfc
	s_sub_i32 s4, s4, s5
	s_sext_i32_i16 s7, s7
	s_sext_i32_i8 s4, s4
	s_add_i32 s6, s6, s4
	s_ashr_i32 s4, s7, 2
.LBB0_412:
	s_andn2_b64 vcc, exec, s[2:3]
	s_cbranch_vccnz .LBB0_520
	v_lshrrev_b32_e32 v2, 1, v212
	s_waitcnt vmcnt(0)
	v_and_b32_e32 v11, 24, v2
	v_lshrrev_b32_e32 v2, 5, v212
	v_and_b32_e32 v2, 4, v2
	v_bfe_u32 v3, v212, 2, 2
	v_lshlrev_b32_e32 v0, 4, v212
	v_and_b32_e32 v1, 32, v212
	v_bfe_u32 v10, v212, 2, 4
	v_or3_b32 v2, v2, v3, v11
	v_lshrrev_b32_e32 v3, 3, v212
	s_movk_i32 s2, 0x70
	v_bitop3_b32 v8, v0, v1, 48 bitop3:0x6c
	v_and_b32_e32 v9, 64, v212
	v_and_or_b32 v4, v3, s2, v10
	s_movk_i32 s2, 0x60
	v_add_u32_e32 v12, 0x2000, v0
	v_or_b32_e32 v1, v8, v9
	v_and_or_b32 v3, v3, s2, v2
	v_lshrrev_b32_e32 v0, 7, v12
	s_movk_i32 s2, 0xf0
	s_add_u32 s40, s88, 0xa00000
	v_lshl_or_b32 v130, v3, 11, v1
	v_and_or_b32 v3, v0, s2, v10
	s_movk_i32 s2, 0xe0
	s_addc_u32 s41, s89, 0
	v_and_or_b32 v0, v0, s2, v2
	s_lshr_b32 s2, s33, 6
	s_ashr_i32 s7, s6, 31
	s_ashr_i32 s5, s4, 31
	s_lshr_b32 s3, s33, 8
	s_lshl_b32 s42, s2, 10
	s_lshl_b64 s[8:9], s[6:7], 19
	s_lshl_b64 s[10:11], s[4:5], 19
	s_add_u32 s24, s40, s10
	s_addc_u32 s25, s41, s11
	s_add_i32 s43, s42, 0
	s_add_i32 m0, s43, 0x10000
	v_lshl_or_b32 v134, v0, 11, v1
	global_load_lds_dwordx4 v130, s[24:25]
	s_add_i32 m0, s43, 0x12000
	s_add_u32 s22, s74, s8
	v_lshl_or_b32 v128, v4, 11, v1
	global_load_lds_dwordx4 v134, s[24:25]
	s_addc_u32 s23, s75, s9
	s_mov_b32 m0, s43
	s_add_i32 s44, s43, 0x2000
	v_lshl_or_b32 v132, v3, 11, v1
	global_load_lds_dwordx4 v128, s[22:23]
	s_mov_b32 m0, s44
	s_add_u32 s8, s24, 0x40000
	global_load_lds_dwordx4 v132, s[22:23]
	s_addc_u32 s9, s25, 0
	s_add_i32 m0, s43, 0x14000
	v_mov_b32_e32 v137, 0
	global_load_lds_dwordx4 v130, s[8:9]
	s_add_i32 m0, s43, 0x16000
	v_mov_b32_e32 v131, v137
	global_load_lds_dwordx4 v134, s[8:9]
	s_add_u32 s8, s22, 0x40000
	s_addc_u32 s9, s23, 0
	s_add_i32 s45, s43, 0x4000
	s_mov_b32 m0, s45
	s_add_i32 s46, s43, 0x6000
	global_load_lds_dwordx4 v128, s[8:9]
	s_mov_b32 m0, s46
	v_mov_b32_e32 v135, v137
	global_load_lds_dwordx4 v132, s[8:9]
	s_branch .Lp4n_join
.Lp4n_start:
	s_cmpk_lt_i32 s84, 0x700
	s_cselect_b64 s[2:3], -1, 0
	s_cmpk_gt_i32 s84, 0x6ff
	v_readfirstlane_b32 s33, v212
	s_cbranch_scc1 .Lp4n_412
	s_ashr_i32 s4, s84, 31
	s_lshr_b32 s4, s4, 29
	s_add_i32 s4, s84, s4
	s_ashr_i32 s5, s4, 3
	s_and_b32 s4, s4, -8
	s_sub_i32 s4, s84, s4
	s_cmp_lt_i32 s4, 0
	s_movk_i32 s6, 0xe1
	s_cselect_b32 s6, s6, 0xe0
	s_mul_i32 s4, s4, s6
	s_add_i32 s4, s4, s5
	s_mul_hi_i32 s5, s4, 0x92492493
	s_add_i32 s5, s5, s4
	s_lshr_b32 s6, s5, 31
	s_ashr_i32 s5, s5, 6
	s_add_i32 s5, s5, s6
	s_lshl_b32 s6, s5, 2
	s_mulk_i32 s5, 0x70
	s_sub_i32 s4, s4, s5
	s_bfe_i32 s5, s4, 0x80000
	s_bfe_u32 s5, s5, 0x2000d
	s_add_i32 s5, s4, s5
	s_bfe_i32 s7, s5, 0x80000
	s_and_b32 s5, s5, 0xfc
	s_sub_i32 s4, s4, s5
	s_sext_i32_i16 s7, s7
	s_sext_i32_i8 s4, s4
	s_add_i32 s6, s6, s4
	s_ashr_i32 s4, s7, 2
.Lp4n_412:
	s_andn2_b64 vcc, exec, s[2:3]
	s_cbranch_vccnz .LBB0_520
	v_lshrrev_b32_e32 v2, 1, v212
	s_waitcnt vmcnt(0)
	v_and_b32_e32 v11, 24, v2
	v_lshrrev_b32_e32 v2, 5, v212
	v_and_b32_e32 v2, 4, v2
	v_bfe_u32 v3, v212, 2, 2
	v_lshlrev_b32_e32 v0, 4, v212
	v_and_b32_e32 v1, 32, v212
	v_bfe_u32 v10, v212, 2, 4
	v_or3_b32 v2, v2, v3, v11
	v_lshrrev_b32_e32 v3, 3, v212
	s_movk_i32 s2, 0x70
	v_bitop3_b32 v8, v0, v1, 48 bitop3:0x6c
	v_and_b32_e32 v9, 64, v212
	v_and_or_b32 v4, v3, s2, v10
	s_movk_i32 s2, 0x60
	v_add_u32_e32 v12, 0x2000, v0
	v_or_b32_e32 v1, v8, v9
	v_and_or_b32 v3, v3, s2, v2
	v_lshrrev_b32_e32 v0, 7, v12
	s_movk_i32 s2, 0xf0
	s_add_u32 s40, s88, 0xa00000
	v_lshl_or_b32 v130, v3, 11, v1
	v_and_or_b32 v3, v0, s2, v10
	s_movk_i32 s2, 0xe0
	s_addc_u32 s41, s89, 0
	v_and_or_b32 v0, v0, s2, v2
	s_lshr_b32 s2, s33, 6
	s_ashr_i32 s7, s6, 31
	s_ashr_i32 s5, s4, 31
	s_lshr_b32 s3, s33, 8
	s_lshl_b32 s42, s2, 10
	s_lshl_b64 s[8:9], s[6:7], 19
	s_lshl_b64 s[10:11], s[4:5], 19
	s_add_u32 s24, s40, s10
	s_addc_u32 s25, s41, s11
	s_add_i32 s43, s42, 0
	s_add_i32 m0, s43, 0x10000
	v_lshl_or_b32 v134, v0, 11, v1
	s_add_i32 m0, s43, 0x12000
	s_add_u32 s22, s74, s8
	v_lshl_or_b32 v128, v4, 11, v1
	s_addc_u32 s23, s75, s9
	s_mov_b32 m0, s43
	s_add_i32 s44, s43, 0x2000
	v_lshl_or_b32 v132, v3, 11, v1
	s_mov_b32 m0, s44
	s_add_u32 s8, s24, 0x40000
	s_addc_u32 s9, s25, 0
	s_add_i32 m0, s43, 0x14000
	v_mov_b32_e32 v137, 0
	s_add_i32 m0, s43, 0x16000
	v_mov_b32_e32 v131, v137
	s_add_u32 s8, s22, 0x40000
	s_addc_u32 s9, s23, 0
	s_add_i32 s45, s43, 0x4000
	s_mov_b32 m0, s45
	s_add_i32 s46, s43, 0x6000
	s_mov_b32 m0, s46
	v_mov_b32_e32 v135, v137
.Lp4n_join:
	s_waitcnt lgkmcnt(0)
	v_mov_b32_e32 v129, v137
	v_mov_b32_e32 v133, v137
	s_mov_b32 s9, 0
	v_lshl_add_u64 v[6:7], s[24:25], 0, v[130:131]
	v_lshl_add_u64 v[4:5], s[24:25], 0, v[134:135]
	v_lshl_add_u64 v[2:3], s[22:23], 0, v[128:129]
	s_cmp_lg_u32 s3, 1
	v_lshl_add_u64 v[0:1], s[22:23], 0, v[132:133]
	s_cbranch_scc1 .LBB0_415
	s_barrier
